# v44 + attention PV first LDS reads hoisted above the softmax exp section (2 of 4 loops)
# speedup vs baseline: 1.0055x; 1.0055x over previous
; __device__ __forceinline__ unsigned cvt_pk_bf16(float lo, float hi) { unsigned r; asm volatile("v_cvt_pk_bf16_f32 %0, %1, %2" : "=v"(r) : "v"(lo), "v"(hi)); return r; }
; #define LAS __attribute__((address_space(3)))
; template <bool MLA, bool grpB>
; __device__ __forceinline__ void attn_unit_g(LAS unsigned char* lds, const AttnPtrs& P, int b, int h, int qblk) {
;     ...
;         float ps = 0.f;
; #pragma unroll
;         for (int blk = 0; blk < 2; ++blk)
; #pragma unroll
;             for (int r = 0; r < 16; ++r) { const float pv_ = __builtin_amdgcn_exp2f(sc[blk][r] - mref); sc[blk][r] = pv_; ps += pv_; }
;         lrun += ps;
; #pragma unroll
;         for (int blk = 0; blk < 2; ++blk)
; #pragma unroll
;             for (int ks = 0; ks < 2; ++ks) { u32x4 w;
;                 w.x = pg8::cvt_pk_bf16(sc[blk][8 * ks + 0], sc[blk][8 * ks + 1]); w.y = pg8::cvt_pk_bf16(sc[blk][8 * ks + 2], sc[blk][8 * ks + 3]);
;                 w.z = pg8::cvt_pk_bf16(sc[blk][8 * ks + 4], sc[blk][8 * ks + 5]); w.w = pg8::cvt_pk_bf16(sc[blk][8 * ks + 6], sc[blk][8 * ks + 7]);
;                 pb[blk][ks] = __builtin_bit_cast(bf16x8, w); }
;         __builtin_amdgcn_sched_barrier(0);
;     };
;     auto pv = [&](int voff) {
;         const LAS unsigned char* va = lds + varow + voff;
;         bf16x8 a[PFD];
;         auto ld = [&](int i) -> bf16x8 {
;             const int dvb = i & 3, bk = i >> 2, so = ((4 * (bk >> 1) + 2 * hi + (bk & 1)) ^ vswz) * 16;
;             return *(const LAS bf16x8*)(va + 32 * dvb * VROW + so);
;         };
; #pragma unroll
;         for (int i = 0; i < PFD; ++i) a[i] = ld(i);
; #pragma unroll
;         for (int i = 0; i < 16; ++i) {
;             o[i & 3] = __builtin_amdgcn_mfma_f32_32x32x16_bf16(a[i % PFD], pb[i >> 3][(i >> 2) & 1], o[i & 3], 0, 0, 0);
;             if (i + PFD < 16) a[i % PFD] = ld(i + PFD);
;         }
;         __builtin_amdgcn_sched_group_barrier(0x100, PFD, 0);
; #pragma unroll
;         for (int i = 0; i < 16; ++i) { __builtin_amdgcn_sched_group_barrier(0x008, 1, 0); __builtin_amdgcn_sched_group_barrier(0x100, 1, 0); }
;         __builtin_amdgcn_sched_barrier(0);
.LBB0_1151:
	v_add_u32_e32 v246, s12, v167
	v_add_u32_e32 v210, v246, v168
	ds_read_b128 v[196:199], v210
	ds_read_b128 v[202:205], v210 offset:4096
	ds_read_b128 v[206:209], v210 offset:8192
	ds_read_b128 v[210:213], v210 offset:12288
	v_add_u32_e32 v222, v246, v169
	ds_read_b128 v[214:217], v222
	ds_read_b128 v[218:221], v222 offset:4096
	v_sub_f32_e32 v18, v18, v178
	v_exp_f32_e32 v18, v18
	v_sub_f32_e32 v19, v19, v178
	v_exp_f32_e32 v19, v19
	v_sub_f32_e32 v20, v20, v178
	v_exp_f32_e32 v20, v20
	v_sub_f32_e32 v21, v21, v178
	v_exp_f32_e32 v21, v21
	v_sub_f32_e32 v22, v22, v178
	v_add_f32_e32 v179, 0, v18
	v_exp_f32_e32 v22, v22
	v_sub_f32_e32 v23, v23, v178
	v_add_f32_e32 v179, v19, v179
	v_exp_f32_e32 v23, v23
	v_sub_f32_e32 v24, v24, v178
	v_add_f32_e32 v179, v20, v179
	v_exp_f32_e32 v24, v24
	v_sub_f32_e32 v25, v25, v178
	v_add_f32_e32 v179, v21, v179
	v_exp_f32_e32 v25, v25
	v_sub_f32_e32 v26, v26, v178
	v_add_f32_e32 v179, v22, v179
	v_exp_f32_e32 v26, v26
	v_sub_f32_e32 v27, v27, v178
	v_add_f32_e32 v179, v23, v179
	v_exp_f32_e32 v27, v27
	v_sub_f32_e32 v28, v28, v178
	v_add_f32_e32 v179, v24, v179
	v_exp_f32_e32 v28, v28
	v_sub_f32_e32 v29, v29, v178
	v_add_f32_e32 v179, v25, v179
	v_exp_f32_e32 v29, v29
	v_sub_f32_e32 v30, v30, v178
	v_add_f32_e32 v179, v26, v179
	v_exp_f32_e32 v30, v30
	v_sub_f32_e32 v31, v31, v178
	v_add_f32_e32 v179, v27, v179
	v_exp_f32_e32 v31, v31
	v_sub_f32_e32 v32, v32, v178
	v_add_f32_e32 v179, v28, v179
	v_exp_f32_e32 v32, v32
	v_sub_f32_e32 v33, v33, v178
	v_add_f32_e32 v179, v29, v179
	v_exp_f32_e32 v33, v33
	v_sub_f32_e32 v50, v50, v178
	v_add_f32_e32 v179, v30, v179
	v_exp_f32_e32 v50, v50
	v_sub_f32_e32 v51, v51, v178
	v_add_f32_e32 v179, v31, v179
	v_exp_f32_e32 v51, v51
	v_sub_f32_e32 v52, v52, v178
	v_add_f32_e32 v179, v32, v179
	v_exp_f32_e32 v52, v52
	v_sub_f32_e32 v53, v53, v178
	v_add_f32_e32 v179, v33, v179
	v_exp_f32_e32 v53, v53
	v_sub_f32_e32 v54, v54, v178
	v_add_f32_e32 v179, v50, v179
	v_exp_f32_e32 v54, v54
	v_sub_f32_e32 v55, v55, v178
	v_add_f32_e32 v179, v51, v179
	v_exp_f32_e32 v55, v55
	v_sub_f32_e32 v56, v56, v178
	v_add_f32_e32 v179, v52, v179
	v_exp_f32_e32 v56, v56
	v_sub_f32_e32 v57, v57, v178
	v_add_f32_e32 v179, v53, v179
	v_exp_f32_e32 v57, v57
	v_sub_f32_e32 v58, v58, v178
	v_add_f32_e32 v179, v54, v179
	v_exp_f32_e32 v58, v58
	v_sub_f32_e32 v59, v59, v178
	v_add_f32_e32 v179, v55, v179
	v_exp_f32_e32 v59, v59
	v_sub_f32_e32 v60, v60, v178
	v_add_f32_e32 v179, v56, v179
	v_exp_f32_e32 v60, v60
	v_sub_f32_e32 v61, v61, v178
	v_add_f32_e32 v179, v57, v179
	v_exp_f32_e32 v61, v61
	v_sub_f32_e32 v62, v62, v178
	v_add_f32_e32 v179, v58, v179
	v_exp_f32_e32 v62, v62
	v_sub_f32_e32 v63, v63, v178
	v_add_f32_e32 v179, v59, v179
	v_exp_f32_e32 v63, v63
	v_sub_f32_e32 v64, v64, v178
	v_add_f32_e32 v179, v60, v179
	v_exp_f32_e32 v64, v64
	v_sub_f32_e32 v65, v65, v178
	v_add_f32_e32 v179, v61, v179
	v_exp_f32_e32 v65, v65
	v_add_f32_e32 v179, v62, v179
	v_add_f32_e32 v179, v63, v179
	v_add_f32_e32 v179, v64, v179
	v_add_f32_e32 v179, v65, v179
	v_add_f32_e32 v176, v176, v179
	v_cvt_pk_bf16_f32 v180, v18, v19
	v_cvt_pk_bf16_f32 v181, v20, v21
	v_cvt_pk_bf16_f32 v182, v22, v23
	v_cvt_pk_bf16_f32 v183, v24, v25
	v_cvt_pk_bf16_f32 v184, v26, v27
	v_cvt_pk_bf16_f32 v185, v28, v29
	v_cvt_pk_bf16_f32 v186, v30, v31
	v_cvt_pk_bf16_f32 v187, v32, v33
	v_cvt_pk_bf16_f32 v188, v50, v51
	v_cvt_pk_bf16_f32 v189, v52, v53
	v_cvt_pk_bf16_f32 v190, v54, v55
	v_cvt_pk_bf16_f32 v191, v56, v57
	v_cvt_pk_bf16_f32 v192, v58, v59
	v_cvt_pk_bf16_f32 v193, v60, v61
	v_cvt_pk_bf16_f32 v194, v62, v63
	v_cvt_pk_bf16_f32 v195, v64, v65
	s_waitcnt lgkmcnt(5)
	s_setprio 1
	v_mfma_f32_32x32x16_bf16 v[82:97], v[196:199], v[180:183], v[82:97]
	ds_read_b128 v[196:199], v222 offset:8192
	s_waitcnt lgkmcnt(5)
	v_mfma_f32_32x32x16_bf16 v[66:81], v[202:205], v[180:183], v[66:81]
	ds_read_b128 v[202:205], v222 offset:12288
	v_add_u32_e32 v222, v246, v175
	v_add_u32_e32 v179, v246, v177
	s_waitcnt lgkmcnt(5)
	v_mfma_f32_32x32x16_bf16 v[34:49], v[206:209], v[180:183], v[34:49]
	ds_read_b128 v[206:209], v222
	s_waitcnt lgkmcnt(5)
	v_mfma_f32_32x32x16_bf16 v[2:17], v[210:213], v[180:183], v[2:17]
	ds_read_b128 v[180:183], v222 offset:4096
	s_waitcnt lgkmcnt(5)
	v_mfma_f32_32x32x16_bf16 v[82:97], v[214:217], v[184:187], v[82:97]
	ds_read_b128 v[210:213], v222 offset:8192
	s_waitcnt lgkmcnt(5)
	v_mfma_f32_32x32x16_bf16 v[66:81], v[218:221], v[184:187], v[66:81]
	ds_read_b128 v[214:217], v222 offset:12288
	s_waitcnt lgkmcnt(5)
	v_mfma_f32_32x32x16_bf16 v[34:49], v[196:199], v[184:187], v[34:49]
	ds_read_b128 v[196:199], v179
	s_waitcnt lgkmcnt(5)
	v_mfma_f32_32x32x16_bf16 v[2:17], v[202:205], v[184:187], v[2:17]
	ds_read_b128 v[184:187], v179 offset:4096
	s_waitcnt lgkmcnt(5)
	v_mfma_f32_32x32x16_bf16 v[82:97], v[206:209], v[188:191], v[82:97]
	ds_read_b128 v[202:205], v179 offset:8192
	s_waitcnt lgkmcnt(5)
	v_mfma_f32_32x32x16_bf16 v[66:81], v[180:183], v[188:191], v[66:81]
	ds_read_b128 v[180:183], v179 offset:12288
	s_waitcnt lgkmcnt(5)
	v_mfma_f32_32x32x16_bf16 v[34:49], v[210:213], v[188:191], v[34:49]
	s_waitcnt lgkmcnt(4)
	v_mfma_f32_32x32x16_bf16 v[2:17], v[214:217], v[188:191], v[2:17]
	s_waitcnt lgkmcnt(3)
	v_mfma_f32_32x32x16_bf16 v[82:97], v[196:199], v[192:195], v[82:97]
	s_waitcnt lgkmcnt(2)
	v_mfma_f32_32x32x16_bf16 v[66:81], v[184:187], v[192:195], v[66:81]
	s_waitcnt lgkmcnt(1)
	v_mfma_f32_32x32x16_bf16 v[34:49], v[202:205], v[192:195], v[34:49]
	s_waitcnt lgkmcnt(0)
	v_mfma_f32_32x32x16_bf16 v[2:17], v[180:183], v[192:195], v[2:17]
	s_setprio 0

; __device__ __forceinline__ unsigned cvt_pk_bf16(float lo, float hi) { unsigned r; asm volatile("v_cvt_pk_bf16_f32 %0, %1, %2" : "=v"(r) : "v"(lo), "v"(hi)); return r; }
; #define LAS __attribute__((address_space(3)))
; template <bool MLA, bool grpB>
; __device__ __forceinline__ void attn_unit_g(LAS unsigned char* lds, const AttnPtrs& P, int b, int h, int qblk) {
;     ...
;         float ps = 0.f;
; #pragma unroll
;         for (int blk = 0; blk < 2; ++blk)
; #pragma unroll
;             for (int r = 0; r < 16; ++r) { const float pv_ = __builtin_amdgcn_exp2f(sc[blk][r] - mref); sc[blk][r] = pv_; ps += pv_; }
;         lrun += ps;
; #pragma unroll
;         for (int blk = 0; blk < 2; ++blk)
; #pragma unroll
;             for (int ks = 0; ks < 2; ++ks) { u32x4 w;
;                 w.x = pg8::cvt_pk_bf16(sc[blk][8 * ks + 0], sc[blk][8 * ks + 1]); w.y = pg8::cvt_pk_bf16(sc[blk][8 * ks + 2], sc[blk][8 * ks + 3]);
;                 w.z = pg8::cvt_pk_bf16(sc[blk][8 * ks + 4], sc[blk][8 * ks + 5]); w.w = pg8::cvt_pk_bf16(sc[blk][8 * ks + 6], sc[blk][8 * ks + 7]);
;                 pb[blk][ks] = __builtin_bit_cast(bf16x8, w); }
;         __builtin_amdgcn_sched_barrier(0);
;     };
;     auto pv = [&](int voff) {
;         const LAS unsigned char* va = lds + varow + voff;
;         bf16x8 a[PFD];
;         auto ld = [&](int i) -> bf16x8 {
;             const int dvb = i & 3, bk = i >> 2, so = ((4 * (bk >> 1) + 2 * hi + (bk & 1)) ^ vswz) * 16;
;             return *(const LAS bf16x8*)(va + 32 * dvb * VROW + so);
;         };
; #pragma unroll
;         for (int i = 0; i < PFD; ++i) a[i] = ld(i);
; #pragma unroll
;         for (int i = 0; i < 16; ++i) {
;             o[i & 3] = __builtin_amdgcn_mfma_f32_32x32x16_bf16(a[i % PFD], pb[i >> 3][(i >> 2) & 1], o[i & 3], 0, 0, 0);
;             if (i + PFD < 16) a[i % PFD] = ld(i + PFD);
;         }
;         __builtin_amdgcn_sched_group_barrier(0x100, PFD, 0);
; #pragma unroll
;         for (int i = 0; i < 16; ++i) { __builtin_amdgcn_sched_group_barrier(0x008, 1, 0); __builtin_amdgcn_sched_group_barrier(0x100, 1, 0); }
;         __builtin_amdgcn_sched_barrier(0);
.LBB0_1268:
	v_add_u32_e32 v246, s54, v175
	v_add_u32_e32 v14, v246, v176
	ds_read_b128 v[186:189], v14
	ds_read_b128 v[190:193], v14 offset:4096
	ds_read_b128 v[194:197], v14 offset:8192
	ds_read_b128 v[202:205], v14 offset:12288
	v_add_u32_e32 v15, v246, v177
	ds_read_b128 v[206:209], v15
	ds_read_b128 v[210:213], v15 offset:4096
	v_sub_f32_e32 v0, v16, v181
	v_exp_f32_e32 v16, v0
	v_sub_f32_e32 v0, v17, v181
	v_exp_f32_e32 v17, v0
	v_sub_f32_e32 v0, v18, v181
	v_exp_f32_e32 v18, v0
	v_sub_f32_e32 v0, v19, v181
	v_exp_f32_e32 v19, v0
	v_sub_f32_e32 v2, v20, v181
	v_add_f32_e32 v0, 0, v16
	v_exp_f32_e32 v20, v2
	v_sub_f32_e32 v2, v21, v181
	v_add_f32_e32 v0, v17, v0
	v_exp_f32_e32 v21, v2
	v_sub_f32_e32 v2, v22, v181
	v_add_f32_e32 v0, v18, v0
	v_exp_f32_e32 v22, v2
	v_sub_f32_e32 v2, v23, v181
	v_add_f32_e32 v0, v19, v0
	v_exp_f32_e32 v23, v2
	v_sub_f32_e32 v2, v24, v181
	v_add_f32_e32 v0, v20, v0
	v_exp_f32_e32 v24, v2
	v_sub_f32_e32 v2, v25, v181
	v_add_f32_e32 v0, v21, v0
	v_exp_f32_e32 v25, v2
	v_sub_f32_e32 v2, v26, v181
	v_add_f32_e32 v0, v22, v0
	v_exp_f32_e32 v26, v2
	v_sub_f32_e32 v2, v27, v181
	v_add_f32_e32 v0, v23, v0
	v_exp_f32_e32 v27, v2
	v_sub_f32_e32 v2, v28, v181
	v_add_f32_e32 v0, v24, v0
	v_exp_f32_e32 v28, v2
	v_sub_f32_e32 v2, v29, v181
	v_add_f32_e32 v0, v25, v0
	v_exp_f32_e32 v29, v2
	v_sub_f32_e32 v2, v30, v181
	v_add_f32_e32 v0, v26, v0
	v_exp_f32_e32 v30, v2
	v_sub_f32_e32 v2, v31, v181
	v_add_f32_e32 v0, v27, v0
	v_exp_f32_e32 v31, v2
	v_sub_f32_e32 v2, v32, v181
	v_add_f32_e32 v0, v28, v0
	v_exp_f32_e32 v32, v2
	v_sub_f32_e32 v2, v33, v181
	v_add_f32_e32 v0, v29, v0
	v_exp_f32_e32 v33, v2
	v_sub_f32_e32 v2, v34, v181
	v_add_f32_e32 v0, v30, v0
	v_exp_f32_e32 v34, v2
	v_sub_f32_e32 v2, v35, v181
	v_add_f32_e32 v0, v31, v0
	v_exp_f32_e32 v35, v2
	v_sub_f32_e32 v2, v36, v181
	v_add_f32_e32 v0, v32, v0
	v_exp_f32_e32 v36, v2
	v_sub_f32_e32 v2, v37, v181
	v_add_f32_e32 v0, v33, v0
	v_exp_f32_e32 v37, v2
	v_sub_f32_e32 v2, v38, v181
	v_add_f32_e32 v0, v34, v0
	v_exp_f32_e32 v38, v2
	v_sub_f32_e32 v2, v39, v181
	v_add_f32_e32 v0, v35, v0
	v_exp_f32_e32 v39, v2
	v_sub_f32_e32 v2, v40, v181
	v_add_f32_e32 v0, v36, v0
	v_exp_f32_e32 v40, v2
	v_sub_f32_e32 v2, v41, v181
	v_add_f32_e32 v0, v37, v0
	v_exp_f32_e32 v41, v2
	v_sub_f32_e32 v2, v42, v181
	v_add_f32_e32 v0, v38, v0
	v_exp_f32_e32 v42, v2
	v_sub_f32_e32 v2, v43, v181
	v_add_f32_e32 v0, v39, v0
	v_exp_f32_e32 v43, v2
	v_sub_f32_e32 v2, v44, v181
	v_add_f32_e32 v0, v40, v0
	v_exp_f32_e32 v44, v2
	v_sub_f32_e32 v2, v45, v181
	v_add_f32_e32 v0, v41, v0
	v_exp_f32_e32 v45, v2
	v_sub_f32_e32 v2, v46, v181
	v_add_f32_e32 v0, v42, v0
	v_exp_f32_e32 v46, v2
	v_sub_f32_e32 v2, v47, v181
	v_add_f32_e32 v0, v43, v0
	v_exp_f32_e32 v47, v2
	v_add_f32_e32 v0, v44, v0
	v_add_f32_e32 v0, v45, v0
	v_add_f32_e32 v0, v46, v0
	v_add_f32_e32 v0, v47, v0
	v_add_f32_e32 v180, v180, v0
	v_cvt_pk_bf16_f32 v2, v16, v17
	v_cvt_pk_bf16_f32 v3, v18, v19
	v_cvt_pk_bf16_f32 v4, v20, v21
	v_cvt_pk_bf16_f32 v5, v22, v23
	v_cvt_pk_bf16_f32 v6, v24, v25
	v_cvt_pk_bf16_f32 v7, v26, v27
	v_cvt_pk_bf16_f32 v8, v28, v29
	v_cvt_pk_bf16_f32 v9, v30, v31
	v_cvt_pk_bf16_f32 v10, v32, v33
	v_cvt_pk_bf16_f32 v11, v34, v35
	v_cvt_pk_bf16_f32 v12, v36, v37
	v_cvt_pk_bf16_f32 v13, v38, v39
	v_cvt_pk_bf16_f32 v182, v40, v41
	v_cvt_pk_bf16_f32 v183, v42, v43
	v_cvt_pk_bf16_f32 v184, v44, v45
	v_cvt_pk_bf16_f32 v185, v46, v47
	v_add_u32_e32 v14, v246, v178
	v_add_u32_e32 v0, v246, v179
	s_waitcnt lgkmcnt(5)
	s_setprio 1
	v_mfma_f32_32x32x16_bf16 v[96:111], v[186:189], v[2:5], v[96:111]
	ds_read_b128 v[186:189], v15 offset:8192
	s_waitcnt lgkmcnt(5)
	v_mfma_f32_32x32x16_bf16 v[80:95], v[190:193], v[2:5], v[80:95]
	ds_read_b128 v[190:193], v15 offset:12288
	s_waitcnt lgkmcnt(5)
	v_mfma_f32_32x32x16_bf16 v[64:79], v[194:197], v[2:5], v[64:79]
	ds_read_b128 v[194:197], v14
	s_waitcnt lgkmcnt(5)
	v_mfma_f32_32x32x16_bf16 v[48:63], v[202:205], v[2:5], v[48:63]
	ds_read_b128 v[2:5], v14 offset:4096
	s_waitcnt lgkmcnt(5)
	v_mfma_f32_32x32x16_bf16 v[96:111], v[206:209], v[6:9], v[96:111]
	ds_read_b128 v[202:205], v14 offset:8192
	s_waitcnt lgkmcnt(5)
	v_mfma_f32_32x32x16_bf16 v[80:95], v[210:213], v[6:9], v[80:95]
	ds_read_b128 v[206:209], v14 offset:12288
	s_waitcnt lgkmcnt(5)
	v_mfma_f32_32x32x16_bf16 v[64:79], v[186:189], v[6:9], v[64:79]
	ds_read_b128 v[186:189], v0
	s_waitcnt lgkmcnt(5)
	v_mfma_f32_32x32x16_bf16 v[48:63], v[190:193], v[6:9], v[48:63]
	ds_read_b128 v[6:9], v0 offset:4096
	s_waitcnt lgkmcnt(5)
	v_mfma_f32_32x32x16_bf16 v[96:111], v[194:197], v[10:13], v[96:111]
	ds_read_b128 v[190:193], v0 offset:8192
	s_waitcnt lgkmcnt(5)
	v_mfma_f32_32x32x16_bf16 v[80:95], v[2:5], v[10:13], v[80:95]
	ds_read_b128 v[2:5], v0 offset:12288
	s_waitcnt lgkmcnt(5)
	v_mfma_f32_32x32x16_bf16 v[64:79], v[202:205], v[10:13], v[64:79]
	s_waitcnt lgkmcnt(4)
	v_mfma_f32_32x32x16_bf16 v[48:63], v[206:209], v[10:13], v[48:63]
	s_waitcnt lgkmcnt(3)
	v_mfma_f32_32x32x16_bf16 v[96:111], v[186:189], v[182:185], v[96:111]
	s_waitcnt lgkmcnt(2)
	v_mfma_f32_32x32x16_bf16 v[80:95], v[6:9], v[182:185], v[80:95]
	s_waitcnt lgkmcnt(1)
	v_mfma_f32_32x32x16_bf16 v[64:79], v[190:193], v[182:185], v[64:79]
	s_waitcnt lgkmcnt(0)
	v_mfma_f32_32x32x16_bf16 v[48:63], v[2:5], v[182:185], v[48:63]
	s_setprio 0
